# tile-setup vmcnt(0) drains removed in P7/P8/P9/P10/P11 (they protected accumulator registers the old epilogues used as load destinations)
# speedup vs baseline: 1.0032x; 1.0032x over previous
;     __device__ bool next(int i, Unit& u) const { Unit b; if (!base.next(i / 3, b)) return false; u.pm = b.pm; u.pn = b.pn + 4 * (i % 3); return true; }
;     __device__ bool next(int i, Unit& u) const { Unit b; if (!base.next(i / 3, b)) return false; const int br = i % 3; u.pm = b.pm + 64 * br; u.pn = b.pn + 4 * br; return true; }
; template <class Epi, class Sched, bool ALIGN_EPI = false, bool SP2 = false>
; __device__ __forceinline__ void gemm_phase(PG8_LAS unsigned char* lds, const Gemm g, const Sched& S, const Epi& E) {
;     ...
;         const bool has_next = S.next(ui + 1, nxt);
;         const char* nA = has_next ? (const char*)g.A + (size_t)nxt.pm * tstep : cA; const char* nB = has_next ? (const char*)g.Bt + (size_t)nxt.pn * tstep : cB;
;         for (int t = 0; t < nt; t += 2) {
;             const bool last = (t == nt - 2);
;             const char* a1 = cA + (size_t)(t + 1) * kstep;
;             const char* a2 = last ? nA : cA + (size_t)(t + 2) * kstep; const char* b2 = last ? nB : cB + (size_t)(t + 2) * kstep;
;             const char* a3 = a2 + kstep; const char* b3 = b2 + kstep;
;     ...
; #pragma unroll
;         for (int a = 0; a < 2; ++a)
; #pragma unroll
;             for (int b = 0; b < 2; ++b)
; #pragma unroll
;                 for (int m = 0; m < 4; ++m)
; #pragma unroll
;                     for (int n = 0; n < 2; ++n) acc[a][b][m][n] = (f32x4){0.f, 0.f, 0.f, 0.f};
.LBB0_1598:
	s_ashr_i32 s21, s20, 31
	s_lshl_b64 s[12:13], s[20:21], 19
	s_add_u32 s24, s33, s12
	s_addc_u32 s25, s36, s13
	s_and_b64 s[12:13], s[2:3], exec
	s_cselect_b32 s12, s25, s41
	s_cselect_b32 s13, s24, s40
	s_ashr_i32 s23, s22, 31
	s_lshl_b64 s[26:27], s[22:23], 19
	s_add_u32 s26, s37, s26
	s_addc_u32 s27, s74, s27
	s_and_b64 s[42:43], s[2:3], exec
	s_cselect_b32 s21, s27, s39
	s_cselect_b32 s23, s26, s38
	s_add_u32 s62, s38, 0x100
	s_addc_u32 s63, s39, 0
	s_add_u32 s38, s40, 0x40080
	v_mov_b32_e32 v0, 0
	s_addc_u32 s39, s41, 0
	s_mov_b32 s64, -2
	v_mov_b32_e32 v1, v0
	v_mov_b32_e32 v2, v0
	v_mov_b32_e32 v3, v0
	v_mov_b32_e32 v4, v0
	v_mov_b32_e32 v5, v0
	v_mov_b32_e32 v6, v0
	v_mov_b32_e32 v7, v0
	v_mov_b32_e32 v16, v0
	v_mov_b32_e32 v17, v0
	v_mov_b32_e32 v18, v0
	v_mov_b32_e32 v19, v0
	v_mov_b32_e32 v20, v0
	v_mov_b32_e32 v21, v0
	v_mov_b32_e32 v22, v0
	v_mov_b32_e32 v23, v0
	v_mov_b32_e32 v32, v0
	v_mov_b32_e32 v33, v0
	v_mov_b32_e32 v34, v0
	v_mov_b32_e32 v35, v0
	v_mov_b32_e32 v36, v0
	v_mov_b32_e32 v37, v0
	v_mov_b32_e32 v38, v0
	v_mov_b32_e32 v39, v0
	v_mov_b32_e32 v48, v0
	v_mov_b32_e32 v49, v0
	v_mov_b32_e32 v50, v0
	v_mov_b32_e32 v51, v0
	v_mov_b32_e32 v52, v0
	v_mov_b32_e32 v53, v0
	v_mov_b32_e32 v54, v0
	v_mov_b32_e32 v55, v0
	v_mov_b32_e32 v8, v0
	v_mov_b32_e32 v9, v0
	v_mov_b32_e32 v10, v0
	v_mov_b32_e32 v11, v0
	v_mov_b32_e32 v12, v0
	v_mov_b32_e32 v13, v0
	v_mov_b32_e32 v14, v0
	v_mov_b32_e32 v15, v0
	v_mov_b32_e32 v24, v0
	v_mov_b32_e32 v25, v0
	v_mov_b32_e32 v26, v0
	v_mov_b32_e32 v27, v0
	v_mov_b32_e32 v28, v0
	v_mov_b32_e32 v29, v0
	v_mov_b32_e32 v30, v0
	v_mov_b32_e32 v31, v0
	v_mov_b32_e32 v40, v0
	v_mov_b32_e32 v41, v0
	v_mov_b32_e32 v42, v0
	v_mov_b32_e32 v43, v0
	v_mov_b32_e32 v44, v0
	v_mov_b32_e32 v45, v0
	v_mov_b32_e32 v46, v0
	v_mov_b32_e32 v47, v0
	v_mov_b32_e32 v56, v0
	v_mov_b32_e32 v57, v0
	v_mov_b32_e32 v58, v0
	v_mov_b32_e32 v59, v0
	v_mov_b32_e32 v60, v0
	v_mov_b32_e32 v61, v0
	v_mov_b32_e32 v62, v0
	v_mov_b32_e32 v63, v0
	v_mov_b32_e32 v64, v0
	v_mov_b32_e32 v65, v0
	v_mov_b32_e32 v66, v0
	v_mov_b32_e32 v67, v0
	v_mov_b32_e32 v68, v0
	v_mov_b32_e32 v69, v0
	v_mov_b32_e32 v70, v0
	v_mov_b32_e32 v71, v0
	v_mov_b32_e32 v96, v0
	v_mov_b32_e32 v97, v0
	v_mov_b32_e32 v98, v0
	v_mov_b32_e32 v99, v0
	v_mov_b32_e32 v100, v0
	v_mov_b32_e32 v101, v0
	v_mov_b32_e32 v102, v0
	v_mov_b32_e32 v103, v0
	v_mov_b32_e32 v112, v0
	v_mov_b32_e32 v113, v0
	v_mov_b32_e32 v114, v0
	v_mov_b32_e32 v115, v0
	v_mov_b32_e32 v116, v0
	v_mov_b32_e32 v117, v0
	v_mov_b32_e32 v118, v0
	v_mov_b32_e32 v119, v0
	v_mov_b32_e32 v128, v0
	v_mov_b32_e32 v129, v0
	v_mov_b32_e32 v130, v0
	v_mov_b32_e32 v131, v0
	v_mov_b32_e32 v132, v0
	v_mov_b32_e32 v133, v0
	v_mov_b32_e32 v134, v0
	v_mov_b32_e32 v135, v0
	v_mov_b32_e32 v76, v0
	v_mov_b32_e32 v77, v0
	v_mov_b32_e32 v78, v0
	v_mov_b32_e32 v79, v0
	v_mov_b32_e32 v80, v0
	v_mov_b32_e32 v81, v0
	v_mov_b32_e32 v82, v0
	v_mov_b32_e32 v83, v0
	v_mov_b32_e32 v104, v0
	v_mov_b32_e32 v105, v0
	v_mov_b32_e32 v106, v0
	v_mov_b32_e32 v107, v0
	v_mov_b32_e32 v108, v0
	v_mov_b32_e32 v109, v0
	v_mov_b32_e32 v110, v0
	v_mov_b32_e32 v111, v0
	v_mov_b32_e32 v120, v0
	v_mov_b32_e32 v121, v0
	v_mov_b32_e32 v122, v0
	v_mov_b32_e32 v123, v0
	v_mov_b32_e32 v124, v0
	v_mov_b32_e32 v125, v0
	v_mov_b32_e32 v126, v0
	v_mov_b32_e32 v127, v0
	v_mov_b32_e32 v136, v0
	v_mov_b32_e32 v137, v0
	v_mov_b32_e32 v138, v0
	v_mov_b32_e32 v139, v0
	v_mov_b32_e32 v140, v0
	v_mov_b32_e32 v141, v0
	v_mov_b32_e32 v142, v0
	v_mov_b32_e32 v143, v0

;     __device__ bool next(int i, Unit& u) const { Unit b; if (!base.next(i / 3, b)) return false; u.pm = b.pm; u.pn = b.pn + 4 * (i % 3); return true; }
;     __device__ bool next(int i, Unit& u) const { Unit b; if (!base.next(i / 3, b)) return false; const int br = i % 3; u.pm = b.pm + 64 * br; u.pn = b.pn + 4 * br; return true; }
; template <class Epi, class Sched, bool ALIGN_EPI = false, bool SP2 = false>
; __device__ __forceinline__ void gemm_phase(PG8_LAS unsigned char* lds, const Gemm g, const Sched& S, const Epi& E) {
;     ...
;         const bool has_next = S.next(ui + 1, nxt);
;         const char* nA = has_next ? (const char*)g.A + (size_t)nxt.pm * tstep : cA; const char* nB = has_next ? (const char*)g.Bt + (size_t)nxt.pn * tstep : cB;
;         for (int t = 0; t < nt; t += 2) {
;             const bool last = (t == nt - 2);
;             const char* a1 = cA + (size_t)(t + 1) * kstep;
;             const char* a2 = last ? nA : cA + (size_t)(t + 2) * kstep; const char* b2 = last ? nB : cB + (size_t)(t + 2) * kstep;
;             const char* a3 = a2 + kstep; const char* b3 = b2 + kstep;
;     ...
;         if (!has_next) break;
; #pragma unroll
;         for (int a = 0; a < 2; ++a)
; #pragma unroll
;             for (int b = 0; b < 2; ++b)
; #pragma unroll
;                 for (int m = 0; m < 4; ++m)
; #pragma unroll
;                     for (int n = 0; n < 2; ++n) acc[a][b][m][n] = (f32x4){0.f, 0.f, 0.f, 0.f};
;         cur = nxt; cA = nA; cB = nB; ++ui;
.LBB0_1625:
	v_mov_b32_e32 v127, 0
	s_andn2_b64 vcc, exec, s[16:17]
	v_mov_b32_e32 v126, v127
	v_mov_b32_e32 v125, v127
	v_mov_b32_e32 v124, v127
	v_mov_b32_e32 v123, v127
	v_mov_b32_e32 v122, v127
	v_mov_b32_e32 v121, v127
	v_mov_b32_e32 v120, v127
	v_mov_b32_e32 v111, v127
	v_mov_b32_e32 v110, v127
	v_mov_b32_e32 v109, v127
	v_mov_b32_e32 v108, v127
	v_mov_b32_e32 v107, v127
	v_mov_b32_e32 v106, v127
	v_mov_b32_e32 v105, v127
	v_mov_b32_e32 v104, v127
	v_mov_b32_e32 v95, v127
	v_mov_b32_e32 v94, v127
	v_mov_b32_e32 v93, v127
	v_mov_b32_e32 v92, v127
	v_mov_b32_e32 v91, v127
	v_mov_b32_e32 v90, v127
	v_mov_b32_e32 v89, v127
	v_mov_b32_e32 v88, v127
	v_mov_b32_e32 v79, v127
	v_mov_b32_e32 v78, v127
	v_mov_b32_e32 v77, v127
	v_mov_b32_e32 v76, v127
	v_mov_b32_e32 v75, v127
	v_mov_b32_e32 v74, v127
	v_mov_b32_e32 v73, v127
	v_mov_b32_e32 v72, v127
	v_mov_b32_e32 v119, v127
	v_mov_b32_e32 v118, v127
	v_mov_b32_e32 v117, v127
	v_mov_b32_e32 v116, v127
	v_mov_b32_e32 v115, v127
	v_mov_b32_e32 v114, v127
	v_mov_b32_e32 v113, v127
	v_mov_b32_e32 v112, v127
	v_mov_b32_e32 v103, v127
	v_mov_b32_e32 v102, v127
	v_mov_b32_e32 v101, v127
	v_mov_b32_e32 v100, v127
	v_mov_b32_e32 v99, v127
	v_mov_b32_e32 v98, v127
	v_mov_b32_e32 v97, v127
	v_mov_b32_e32 v96, v127
	v_mov_b32_e32 v87, v127
	v_mov_b32_e32 v86, v127
	v_mov_b32_e32 v85, v127
	v_mov_b32_e32 v84, v127
	v_mov_b32_e32 v83, v127
	v_mov_b32_e32 v82, v127
	v_mov_b32_e32 v81, v127
	v_mov_b32_e32 v80, v127
	v_mov_b32_e32 v71, v127
	v_mov_b32_e32 v70, v127
	v_mov_b32_e32 v69, v127
	v_mov_b32_e32 v68, v127
	v_mov_b32_e32 v67, v127
	v_mov_b32_e32 v66, v127
	v_mov_b32_e32 v65, v127
	v_mov_b32_e32 v64, v127
	v_mov_b32_e32 v63, v127
	v_mov_b32_e32 v62, v127
	v_mov_b32_e32 v61, v127
	v_mov_b32_e32 v60, v127
	v_mov_b32_e32 v59, v127
	v_mov_b32_e32 v58, v127
	v_mov_b32_e32 v57, v127
	v_mov_b32_e32 v56, v127
	v_mov_b32_e32 v47, v127
	v_mov_b32_e32 v46, v127
	v_mov_b32_e32 v45, v127
	v_mov_b32_e32 v44, v127
	v_mov_b32_e32 v43, v127
	v_mov_b32_e32 v42, v127
	v_mov_b32_e32 v41, v127
	v_mov_b32_e32 v40, v127
	v_mov_b32_e32 v31, v127
	v_mov_b32_e32 v30, v127
	v_mov_b32_e32 v29, v127
	v_mov_b32_e32 v28, v127
	v_mov_b32_e32 v27, v127
	v_mov_b32_e32 v26, v127
	v_mov_b32_e32 v25, v127
	v_mov_b32_e32 v24, v127
	v_mov_b32_e32 v15, v127
	v_mov_b32_e32 v14, v127
	v_mov_b32_e32 v13, v127
	v_mov_b32_e32 v12, v127
	v_mov_b32_e32 v11, v127
	v_mov_b32_e32 v10, v127
	v_mov_b32_e32 v9, v127
	v_mov_b32_e32 v8, v127
	v_mov_b32_e32 v55, v127
	v_mov_b32_e32 v54, v127
	v_mov_b32_e32 v53, v127
	v_mov_b32_e32 v52, v127
	v_mov_b32_e32 v51, v127
	v_mov_b32_e32 v50, v127
	v_mov_b32_e32 v49, v127
	v_mov_b32_e32 v48, v127
	v_mov_b32_e32 v39, v127
	v_mov_b32_e32 v38, v127
	v_mov_b32_e32 v37, v127
	v_mov_b32_e32 v36, v127
	v_mov_b32_e32 v35, v127
	v_mov_b32_e32 v34, v127
	v_mov_b32_e32 v33, v127
	v_mov_b32_e32 v32, v127
	v_mov_b32_e32 v23, v127
	v_mov_b32_e32 v22, v127
	v_mov_b32_e32 v21, v127
	v_mov_b32_e32 v20, v127
	v_mov_b32_e32 v19, v127
	v_mov_b32_e32 v18, v127
	v_mov_b32_e32 v17, v127
	v_mov_b32_e32 v16, v127
	v_mov_b32_e32 v7, v127
	v_mov_b32_e32 v6, v127
	v_mov_b32_e32 v5, v127
	v_mov_b32_e32 v4, v127
	v_mov_b32_e32 v3, v127
	v_mov_b32_e32 v2, v127
	v_mov_b32_e32 v1, v127
	v_mov_b32_e32 v0, v127
	s_cbranch_vccnz .LBB0_1628
	s_add_u32 s54, s24, 0x100
	s_addc_u32 s55, s25, 0
	s_add_u32 s4, s26, 0x80
	v_mov_b32_e32 v0, 0
	s_addc_u32 s5, s27, 0
	s_mov_b32 s24, 0
	v_mov_b32_e32 v1, v0
	v_mov_b32_e32 v2, v0
	v_mov_b32_e32 v3, v0
	v_mov_b32_e32 v4, v0
	v_mov_b32_e32 v5, v0
	v_mov_b32_e32 v6, v0
	v_mov_b32_e32 v7, v0
	v_mov_b32_e32 v16, v0
	v_mov_b32_e32 v17, v0
	v_mov_b32_e32 v18, v0
	v_mov_b32_e32 v19, v0
	v_mov_b32_e32 v20, v0
	v_mov_b32_e32 v21, v0
	v_mov_b32_e32 v22, v0
	v_mov_b32_e32 v23, v0
	v_mov_b32_e32 v32, v0
	v_mov_b32_e32 v33, v0
	v_mov_b32_e32 v34, v0
	v_mov_b32_e32 v35, v0
	v_mov_b32_e32 v36, v0
	v_mov_b32_e32 v37, v0
	v_mov_b32_e32 v38, v0
	v_mov_b32_e32 v39, v0
	v_mov_b32_e32 v48, v0
	v_mov_b32_e32 v49, v0
	v_mov_b32_e32 v50, v0
	v_mov_b32_e32 v51, v0
	v_mov_b32_e32 v52, v0
	v_mov_b32_e32 v53, v0
	v_mov_b32_e32 v54, v0
	v_mov_b32_e32 v55, v0
	v_mov_b32_e32 v8, v0
	v_mov_b32_e32 v9, v0
	v_mov_b32_e32 v10, v0
	v_mov_b32_e32 v11, v0
	v_mov_b32_e32 v12, v0
	v_mov_b32_e32 v13, v0
	v_mov_b32_e32 v14, v0
	v_mov_b32_e32 v15, v0
	v_mov_b32_e32 v24, v0
	v_mov_b32_e32 v25, v0
	v_mov_b32_e32 v26, v0
	v_mov_b32_e32 v27, v0
	v_mov_b32_e32 v28, v0
	v_mov_b32_e32 v29, v0
	v_mov_b32_e32 v30, v0
	v_mov_b32_e32 v31, v0
	v_mov_b32_e32 v40, v0
	v_mov_b32_e32 v41, v0
	v_mov_b32_e32 v42, v0
	v_mov_b32_e32 v43, v0
	v_mov_b32_e32 v44, v0
	v_mov_b32_e32 v45, v0
	v_mov_b32_e32 v46, v0
	v_mov_b32_e32 v47, v0
	v_mov_b32_e32 v56, v0
	v_mov_b32_e32 v57, v0
	v_mov_b32_e32 v58, v0
	v_mov_b32_e32 v59, v0
	v_mov_b32_e32 v60, v0
	v_mov_b32_e32 v61, v0
	v_mov_b32_e32 v62, v0
	v_mov_b32_e32 v63, v0
	v_mov_b32_e32 v64, v0
	v_mov_b32_e32 v65, v0
	v_mov_b32_e32 v66, v0
	v_mov_b32_e32 v67, v0
	v_mov_b32_e32 v68, v0
	v_mov_b32_e32 v69, v0
	v_mov_b32_e32 v70, v0
	v_mov_b32_e32 v71, v0
	v_mov_b32_e32 v80, v0
	v_mov_b32_e32 v81, v0
	v_mov_b32_e32 v82, v0
	v_mov_b32_e32 v83, v0
	v_mov_b32_e32 v84, v0
	v_mov_b32_e32 v85, v0
	v_mov_b32_e32 v86, v0
	v_mov_b32_e32 v87, v0
	v_mov_b32_e32 v96, v0
	v_mov_b32_e32 v97, v0
	v_mov_b32_e32 v98, v0
	v_mov_b32_e32 v99, v0
	v_mov_b32_e32 v100, v0
	v_mov_b32_e32 v101, v0
	v_mov_b32_e32 v102, v0
	v_mov_b32_e32 v103, v0
	v_mov_b32_e32 v112, v0
	v_mov_b32_e32 v113, v0
	v_mov_b32_e32 v114, v0
	v_mov_b32_e32 v115, v0
	v_mov_b32_e32 v116, v0
	v_mov_b32_e32 v117, v0
	v_mov_b32_e32 v118, v0
	v_mov_b32_e32 v119, v0
	v_mov_b32_e32 v72, v0
	v_mov_b32_e32 v73, v0
	v_mov_b32_e32 v74, v0
	v_mov_b32_e32 v75, v0
	v_mov_b32_e32 v76, v0
	v_mov_b32_e32 v77, v0
	v_mov_b32_e32 v78, v0
	v_mov_b32_e32 v79, v0
	v_mov_b32_e32 v88, v0
	v_mov_b32_e32 v89, v0
	v_mov_b32_e32 v90, v0
	v_mov_b32_e32 v91, v0
	v_mov_b32_e32 v92, v0
	v_mov_b32_e32 v93, v0
	v_mov_b32_e32 v94, v0
	v_mov_b32_e32 v95, v0
	v_mov_b32_e32 v104, v0
	v_mov_b32_e32 v105, v0
	v_mov_b32_e32 v106, v0
	v_mov_b32_e32 v107, v0
	v_mov_b32_e32 v108, v0
	v_mov_b32_e32 v109, v0
	v_mov_b32_e32 v110, v0
	v_mov_b32_e32 v111, v0
	v_mov_b32_e32 v120, v0
	v_mov_b32_e32 v121, v0
	v_mov_b32_e32 v122, v0
	v_mov_b32_e32 v123, v0
	v_mov_b32_e32 v124, v0
	v_mov_b32_e32 v125, v0
	v_mov_b32_e32 v126, v0
	v_mov_b32_e32 v127, v0

;     __device__ bool next(int i, Unit& u) const { Unit b; if (!base.next(i / 3, b)) return false; u.pm = b.pm; u.pn = b.pn + 4 * (i % 3); return true; }
;     __device__ bool next(int i, Unit& u) const { Unit b; if (!base.next(i / 3, b)) return false; const int br = i % 3; u.pm = b.pm + 64 * br; u.pn = b.pn + 4 * br; return true; }
; template <class Epi, class Sched, bool ALIGN_EPI = false, bool SP2 = false>
; __device__ __forceinline__ void gemm_phase(PG8_LAS unsigned char* lds, const Gemm g, const Sched& S, const Epi& E) {
;     ...
;         const bool has_next = S.next(ui + 1, nxt);
;         const char* nA = has_next ? (const char*)g.A + (size_t)nxt.pm * tstep : cA; const char* nB = has_next ? (const char*)g.Bt + (size_t)nxt.pn * tstep : cB;
;         for (int t = 0; t < nt; t += 2) {
;             const bool last = (t == nt - 2);
;             const char* a1 = cA + (size_t)(t + 1) * kstep;
;             const char* a2 = last ? nA : cA + (size_t)(t + 2) * kstep; const char* b2 = last ? nB : cB + (size_t)(t + 2) * kstep;
;             const char* a3 = a2 + kstep; const char* b3 = b2 + kstep;
;     ...
; #pragma unroll
;         for (int a = 0; a < 2; ++a)
; #pragma unroll
;             for (int b = 0; b < 2; ++b)
; #pragma unroll
;                 for (int m = 0; m < 4; ++m)
; #pragma unroll
;                     for (int n = 0; n < 2; ++n) acc[a][b][m][n] = (f32x4){0.f, 0.f, 0.f, 0.f};
.LBB0_1735:
	s_ashr_i32 s23, s22, 31
	s_lshl_b64 s[12:13], s[22:23], 19
	s_add_u32 s24, s28, s12
	s_addc_u32 s25, s29, s13
	s_and_b64 s[12:13], s[4:5], exec
	s_cselect_b32 s12, s25, s39
	s_cselect_b32 s13, s24, s38
	s_ashr_i32 s21, s20, 31
	s_lshl_b64 s[26:27], s[20:21], 19
	s_add_u32 s26, s33, s26
	s_addc_u32 s27, s44, s27
	s_and_b64 s[42:43], s[4:5], exec
	s_cselect_b32 s21, s27, s41
	s_cselect_b32 s23, s26, s40
	s_add_u32 s38, s38, 0x40080
	s_addc_u32 s39, s39, 0
	s_add_u32 s56, s40, 0x100
	v_mov_b32_e32 v0, 0
	s_addc_u32 s57, s41, 0
	s_mov_b32 s58, -2
	s_waitcnt lgkmcnt(0)
	v_mov_b32_e32 v1, v0
	v_mov_b32_e32 v2, v0
	v_mov_b32_e32 v3, v0
	v_mov_b32_e32 v4, v0
	v_mov_b32_e32 v5, v0
	v_mov_b32_e32 v6, v0
	v_mov_b32_e32 v7, v0
	v_mov_b32_e32 v16, v0
	v_mov_b32_e32 v17, v0
	v_mov_b32_e32 v18, v0
	v_mov_b32_e32 v19, v0
	v_mov_b32_e32 v20, v0
	v_mov_b32_e32 v21, v0
	v_mov_b32_e32 v22, v0
	v_mov_b32_e32 v23, v0
	v_mov_b32_e32 v32, v0
	v_mov_b32_e32 v33, v0
	v_mov_b32_e32 v34, v0
	v_mov_b32_e32 v35, v0
	v_mov_b32_e32 v36, v0
	v_mov_b32_e32 v37, v0
	v_mov_b32_e32 v38, v0
	v_mov_b32_e32 v39, v0
	v_mov_b32_e32 v48, v0
	v_mov_b32_e32 v49, v0
	v_mov_b32_e32 v50, v0
	v_mov_b32_e32 v51, v0
	v_mov_b32_e32 v52, v0
	v_mov_b32_e32 v53, v0
	v_mov_b32_e32 v54, v0
	v_mov_b32_e32 v55, v0
	v_mov_b32_e32 v8, v0
	v_mov_b32_e32 v9, v0
	v_mov_b32_e32 v10, v0
	v_mov_b32_e32 v11, v0
	v_mov_b32_e32 v12, v0
	v_mov_b32_e32 v13, v0
	v_mov_b32_e32 v14, v0
	v_mov_b32_e32 v15, v0
	v_mov_b32_e32 v24, v0
	v_mov_b32_e32 v25, v0
	v_mov_b32_e32 v26, v0
	v_mov_b32_e32 v27, v0
	v_mov_b32_e32 v28, v0
	v_mov_b32_e32 v29, v0
	v_mov_b32_e32 v30, v0
	v_mov_b32_e32 v31, v0
	v_mov_b32_e32 v40, v0
	v_mov_b32_e32 v41, v0
	v_mov_b32_e32 v42, v0
	v_mov_b32_e32 v43, v0
	v_mov_b32_e32 v44, v0
	v_mov_b32_e32 v45, v0
	v_mov_b32_e32 v46, v0
	v_mov_b32_e32 v47, v0
	v_mov_b32_e32 v56, v0
	v_mov_b32_e32 v57, v0
	v_mov_b32_e32 v58, v0
	v_mov_b32_e32 v59, v0
	v_mov_b32_e32 v60, v0
	v_mov_b32_e32 v61, v0
	v_mov_b32_e32 v62, v0
	v_mov_b32_e32 v63, v0
	v_mov_b32_e32 v64, v0
	v_mov_b32_e32 v65, v0
	v_mov_b32_e32 v66, v0
	v_mov_b32_e32 v67, v0
	v_mov_b32_e32 v68, v0
	v_mov_b32_e32 v69, v0
	v_mov_b32_e32 v70, v0
	v_mov_b32_e32 v71, v0
	v_mov_b32_e32 v80, v0
	v_mov_b32_e32 v81, v0
	v_mov_b32_e32 v82, v0
	v_mov_b32_e32 v83, v0
	v_mov_b32_e32 v84, v0
	v_mov_b32_e32 v85, v0
	v_mov_b32_e32 v86, v0
	v_mov_b32_e32 v87, v0
	v_mov_b32_e32 v96, v0
	v_mov_b32_e32 v97, v0
	v_mov_b32_e32 v98, v0
	v_mov_b32_e32 v99, v0
	v_mov_b32_e32 v100, v0
	v_mov_b32_e32 v101, v0
	v_mov_b32_e32 v102, v0
	v_mov_b32_e32 v103, v0
	v_mov_b32_e32 v112, v0
	v_mov_b32_e32 v113, v0
	v_mov_b32_e32 v114, v0
	v_mov_b32_e32 v115, v0
	v_mov_b32_e32 v116, v0
	v_mov_b32_e32 v117, v0
	v_mov_b32_e32 v118, v0
	v_mov_b32_e32 v119, v0
	v_mov_b32_e32 v72, v0
	v_mov_b32_e32 v73, v0
	v_mov_b32_e32 v74, v0
	v_mov_b32_e32 v75, v0
	v_mov_b32_e32 v76, v0
	v_mov_b32_e32 v77, v0
	v_mov_b32_e32 v78, v0
	v_mov_b32_e32 v79, v0
	v_mov_b32_e32 v88, v0
	v_mov_b32_e32 v89, v0
	v_mov_b32_e32 v90, v0
	v_mov_b32_e32 v91, v0
	v_mov_b32_e32 v92, v0
	v_mov_b32_e32 v93, v0
	v_mov_b32_e32 v94, v0
	v_mov_b32_e32 v95, v0
	v_mov_b32_e32 v104, v0
	v_mov_b32_e32 v105, v0
	v_mov_b32_e32 v106, v0
	v_mov_b32_e32 v107, v0
	v_mov_b32_e32 v108, v0
	v_mov_b32_e32 v109, v0
	v_mov_b32_e32 v110, v0
	v_mov_b32_e32 v111, v0
	v_mov_b32_e32 v120, v0
	v_mov_b32_e32 v121, v0
	v_mov_b32_e32 v122, v0
	v_mov_b32_e32 v123, v0
	v_mov_b32_e32 v124, v0
	v_mov_b32_e32 v125, v0
	v_mov_b32_e32 v126, v0
	v_mov_b32_e32 v127, v0

; template <class Epi, class Sched, bool ALIGN_EPI = false, bool SP2 = false>
; __device__ __forceinline__ void gemm_phase(PG8_LAS unsigned char* lds, const Gemm g, const Sched& S, const Epi& E) {
;     ...
;         const char* nA = has_next ? (const char*)g.A + (size_t)nxt.pm * tstep : cA; const char* nB = has_next ? (const char*)g.Bt + (size_t)nxt.pn * tstep : cB;
;         for (int t = 0; t < nt; t += 2) {
;             const bool last = (t == nt - 2);
;             const char* a1 = cA + (size_t)(t + 1) * kstep;
;             const char* a2 = last ? nA : cA + (size_t)(t + 2) * kstep; const char* b2 = last ? nB : cB + (size_t)(t + 2) * kstep;
;             const char* a3 = a2 + kstep; const char* b3 = b2 + kstep;
;     ...
; #pragma unroll
;         for (int a = 0; a < 2; ++a)
; #pragma unroll
;             for (int b = 0; b < 2; ++b)
; #pragma unroll
;                 for (int m = 0; m < 4; ++m)
; #pragma unroll
;                     for (int n = 0; n < 2; ++n) acc[a][b][m][n] = (f32x4){0.f, 0.f, 0.f, 0.f};
.LBB0_1822:
	s_ashr_i32 s19, s18, 31
	s_lshl_b64 s[12:13], s[18:19], 19
	s_add_u32 s20, s33, s12
	s_addc_u32 s21, s38, s13
	s_and_b64 s[12:13], s[2:3], exec
	s_cselect_b32 s12, s21, s35
	s_cselect_b32 s13, s20, s34
	s_ashr_i32 s17, s16, 31
	s_lshl_b64 s[22:23], s[16:17], 19
	s_add_u32 s22, s39, s22
	s_addc_u32 s23, s40, s23
	s_and_b64 s[36:37], s[2:3], exec
	s_cselect_b32 s17, s23, s27
	s_cselect_b32 s19, s22, s26
	s_add_u32 s56, s26, 0x100
	s_addc_u32 s57, s27, 0
	s_add_u32 s26, s34, 0x40080
	v_mov_b32_e32 v0, 0
	s_addc_u32 s27, s35, 0
	s_mov_b32 s58, -2
	v_mov_b32_e32 v1, v0
	v_mov_b32_e32 v2, v0
	v_mov_b32_e32 v3, v0
	v_mov_b32_e32 v4, v0
	v_mov_b32_e32 v5, v0
	v_mov_b32_e32 v6, v0
	v_mov_b32_e32 v7, v0
	v_mov_b32_e32 v16, v0
	v_mov_b32_e32 v17, v0
	v_mov_b32_e32 v18, v0
	v_mov_b32_e32 v19, v0
	v_mov_b32_e32 v20, v0
	v_mov_b32_e32 v21, v0
	v_mov_b32_e32 v22, v0
	v_mov_b32_e32 v23, v0
	v_mov_b32_e32 v32, v0
	v_mov_b32_e32 v33, v0
	v_mov_b32_e32 v34, v0
	v_mov_b32_e32 v35, v0
	v_mov_b32_e32 v36, v0
	v_mov_b32_e32 v37, v0
	v_mov_b32_e32 v38, v0
	v_mov_b32_e32 v39, v0
	v_mov_b32_e32 v48, v0
	v_mov_b32_e32 v49, v0
	v_mov_b32_e32 v50, v0
	v_mov_b32_e32 v51, v0
	v_mov_b32_e32 v52, v0
	v_mov_b32_e32 v53, v0
	v_mov_b32_e32 v54, v0
	v_mov_b32_e32 v55, v0
	v_mov_b32_e32 v8, v0
	v_mov_b32_e32 v9, v0
	v_mov_b32_e32 v10, v0
	v_mov_b32_e32 v11, v0
	v_mov_b32_e32 v12, v0
	v_mov_b32_e32 v13, v0
	v_mov_b32_e32 v14, v0
	v_mov_b32_e32 v15, v0
	v_mov_b32_e32 v24, v0
	v_mov_b32_e32 v25, v0
	v_mov_b32_e32 v26, v0
	v_mov_b32_e32 v27, v0
	v_mov_b32_e32 v28, v0
	v_mov_b32_e32 v29, v0
	v_mov_b32_e32 v30, v0
	v_mov_b32_e32 v31, v0
	v_mov_b32_e32 v40, v0
	v_mov_b32_e32 v41, v0
	v_mov_b32_e32 v42, v0
	v_mov_b32_e32 v43, v0
	v_mov_b32_e32 v44, v0
	v_mov_b32_e32 v45, v0
	v_mov_b32_e32 v46, v0
	v_mov_b32_e32 v47, v0
	v_mov_b32_e32 v56, v0
	v_mov_b32_e32 v57, v0
	v_mov_b32_e32 v58, v0
	v_mov_b32_e32 v59, v0
	v_mov_b32_e32 v60, v0
	v_mov_b32_e32 v61, v0
	v_mov_b32_e32 v62, v0
	v_mov_b32_e32 v63, v0
	v_mov_b32_e32 v64, v0
	v_mov_b32_e32 v65, v0
	v_mov_b32_e32 v66, v0
	v_mov_b32_e32 v67, v0
	v_mov_b32_e32 v68, v0
	v_mov_b32_e32 v69, v0
	v_mov_b32_e32 v70, v0
	v_mov_b32_e32 v71, v0
	v_mov_b32_e32 v80, v0
	v_mov_b32_e32 v81, v0
	v_mov_b32_e32 v82, v0
	v_mov_b32_e32 v83, v0
	v_mov_b32_e32 v84, v0
	v_mov_b32_e32 v85, v0
	v_mov_b32_e32 v86, v0
	v_mov_b32_e32 v87, v0
	v_mov_b32_e32 v96, v0
	v_mov_b32_e32 v97, v0
	v_mov_b32_e32 v98, v0
	v_mov_b32_e32 v99, v0
	v_mov_b32_e32 v100, v0
	v_mov_b32_e32 v101, v0
	v_mov_b32_e32 v102, v0
	v_mov_b32_e32 v103, v0
	v_mov_b32_e32 v112, v0
	v_mov_b32_e32 v113, v0
	v_mov_b32_e32 v114, v0
	v_mov_b32_e32 v115, v0
	v_mov_b32_e32 v116, v0
	v_mov_b32_e32 v117, v0
	v_mov_b32_e32 v118, v0
	v_mov_b32_e32 v119, v0
	v_mov_b32_e32 v72, v0
	v_mov_b32_e32 v73, v0
	v_mov_b32_e32 v74, v0
	v_mov_b32_e32 v75, v0
	v_mov_b32_e32 v76, v0
	v_mov_b32_e32 v77, v0
	v_mov_b32_e32 v78, v0
	v_mov_b32_e32 v79, v0
	v_mov_b32_e32 v88, v0
	v_mov_b32_e32 v89, v0
	v_mov_b32_e32 v90, v0
	v_mov_b32_e32 v91, v0
	v_mov_b32_e32 v92, v0
	v_mov_b32_e32 v93, v0
	v_mov_b32_e32 v94, v0
	v_mov_b32_e32 v95, v0
	v_mov_b32_e32 v104, v0
	v_mov_b32_e32 v105, v0
	v_mov_b32_e32 v106, v0
	v_mov_b32_e32 v107, v0
	v_mov_b32_e32 v108, v0
	v_mov_b32_e32 v109, v0
	v_mov_b32_e32 v110, v0
	v_mov_b32_e32 v111, v0
	v_mov_b32_e32 v120, v0
	v_mov_b32_e32 v121, v0
	v_mov_b32_e32 v122, v0
	v_mov_b32_e32 v123, v0
	v_mov_b32_e32 v124, v0
	v_mov_b32_e32 v125, v0
	v_mov_b32_e32 v126, v0
	v_mov_b32_e32 v127, v0

; template <class Epi, class Sched, bool ALIGN_EPI = false, bool SP2 = false>
; __device__ __forceinline__ void gemm_phase(PG8_LAS unsigned char* lds, const Gemm g, const Sched& S, const Epi& E) {
;     ...
;         const char* nA = has_next ? (const char*)g.A + (size_t)nxt.pm * tstep : cA; const char* nB = has_next ? (const char*)g.Bt + (size_t)nxt.pn * tstep : cB;
;         for (int t = 0; t < nt; t += 2) {
;             const bool last = (t == nt - 2);
;             const char* a1 = cA + (size_t)(t + 1) * kstep;
;             const char* a2 = last ? nA : cA + (size_t)(t + 2) * kstep; const char* b2 = last ? nB : cB + (size_t)(t + 2) * kstep;
;             const char* a3 = a2 + kstep; const char* b3 = b2 + kstep;
;     ...
; #pragma unroll
;         for (int a = 0; a < 2; ++a)
; #pragma unroll
;             for (int b = 0; b < 2; ++b)
; #pragma unroll
;                 for (int m = 0; m < 4; ++m)
; #pragma unroll
;                     for (int n = 0; n < 2; ++n) acc[a][b][m][n] = (f32x4){0.f, 0.f, 0.f, 0.f};
.LBB0_1901:
	s_add_u32 s51, s24, 0x100
	s_addc_u32 s52, s25, 0
	s_add_u32 s24, s26, 0xb0080
	v_mov_b32_e32 v0, 0
	s_addc_u32 s25, s27, 0
	s_mov_b32 s53, -2
	v_mov_b32_e32 v1, v0
	v_mov_b32_e32 v2, v0
	v_mov_b32_e32 v3, v0
	v_mov_b32_e32 v4, v0
	v_mov_b32_e32 v5, v0
	v_mov_b32_e32 v6, v0
	v_mov_b32_e32 v7, v0
	v_mov_b32_e32 v16, v0
	v_mov_b32_e32 v17, v0
	v_mov_b32_e32 v18, v0
	v_mov_b32_e32 v19, v0
	v_mov_b32_e32 v20, v0
	v_mov_b32_e32 v21, v0
	v_mov_b32_e32 v22, v0
	v_mov_b32_e32 v23, v0
	v_mov_b32_e32 v32, v0
	v_mov_b32_e32 v33, v0
	v_mov_b32_e32 v34, v0
	v_mov_b32_e32 v35, v0
	v_mov_b32_e32 v36, v0
	v_mov_b32_e32 v37, v0
	v_mov_b32_e32 v38, v0
	v_mov_b32_e32 v39, v0
	v_mov_b32_e32 v48, v0
	v_mov_b32_e32 v49, v0
	v_mov_b32_e32 v50, v0
	v_mov_b32_e32 v51, v0
	v_mov_b32_e32 v52, v0
	v_mov_b32_e32 v53, v0
	v_mov_b32_e32 v54, v0
	v_mov_b32_e32 v55, v0
	v_mov_b32_e32 v8, v0
	v_mov_b32_e32 v9, v0
	v_mov_b32_e32 v10, v0
	v_mov_b32_e32 v11, v0
	v_mov_b32_e32 v12, v0
	v_mov_b32_e32 v13, v0
	v_mov_b32_e32 v14, v0
	v_mov_b32_e32 v15, v0
	v_mov_b32_e32 v24, v0
	v_mov_b32_e32 v25, v0
	v_mov_b32_e32 v26, v0
	v_mov_b32_e32 v27, v0
	v_mov_b32_e32 v28, v0
	v_mov_b32_e32 v29, v0
	v_mov_b32_e32 v30, v0
	v_mov_b32_e32 v31, v0
	v_mov_b32_e32 v40, v0
	v_mov_b32_e32 v41, v0
	v_mov_b32_e32 v42, v0
	v_mov_b32_e32 v43, v0
	v_mov_b32_e32 v44, v0
	v_mov_b32_e32 v45, v0
	v_mov_b32_e32 v46, v0
	v_mov_b32_e32 v47, v0
	v_mov_b32_e32 v56, v0
	v_mov_b32_e32 v57, v0
	v_mov_b32_e32 v58, v0
	v_mov_b32_e32 v59, v0
	v_mov_b32_e32 v60, v0
	v_mov_b32_e32 v61, v0
	v_mov_b32_e32 v62, v0
	v_mov_b32_e32 v63, v0
	v_mov_b32_e32 v64, v0
	v_mov_b32_e32 v65, v0
	v_mov_b32_e32 v66, v0
	v_mov_b32_e32 v67, v0
	v_mov_b32_e32 v68, v0
	v_mov_b32_e32 v69, v0
	v_mov_b32_e32 v70, v0
	v_mov_b32_e32 v71, v0
	v_mov_b32_e32 v80, v0
	v_mov_b32_e32 v81, v0
	v_mov_b32_e32 v82, v0
	v_mov_b32_e32 v83, v0
	v_mov_b32_e32 v84, v0
	v_mov_b32_e32 v85, v0
	v_mov_b32_e32 v86, v0
	v_mov_b32_e32 v87, v0
	v_mov_b32_e32 v96, v0
	v_mov_b32_e32 v97, v0
	v_mov_b32_e32 v98, v0
	v_mov_b32_e32 v99, v0
	v_mov_b32_e32 v100, v0
	v_mov_b32_e32 v101, v0
	v_mov_b32_e32 v102, v0
	v_mov_b32_e32 v103, v0
	v_mov_b32_e32 v112, v0
	v_mov_b32_e32 v113, v0
	v_mov_b32_e32 v114, v0
	v_mov_b32_e32 v115, v0
	v_mov_b32_e32 v116, v0
	v_mov_b32_e32 v117, v0
	v_mov_b32_e32 v118, v0
	v_mov_b32_e32 v119, v0
	v_mov_b32_e32 v72, v0
	v_mov_b32_e32 v73, v0
	v_mov_b32_e32 v74, v0
	v_mov_b32_e32 v75, v0
	v_mov_b32_e32 v76, v0
	v_mov_b32_e32 v77, v0
	v_mov_b32_e32 v78, v0
	v_mov_b32_e32 v79, v0
	v_mov_b32_e32 v88, v0
	v_mov_b32_e32 v89, v0
	v_mov_b32_e32 v90, v0
	v_mov_b32_e32 v91, v0
	v_mov_b32_e32 v92, v0
	v_mov_b32_e32 v93, v0
	v_mov_b32_e32 v94, v0
	v_mov_b32_e32 v95, v0
	v_mov_b32_e32 v104, v0
	v_mov_b32_e32 v105, v0
	v_mov_b32_e32 v106, v0
	v_mov_b32_e32 v107, v0
	v_mov_b32_e32 v108, v0
	v_mov_b32_e32 v109, v0
	v_mov_b32_e32 v110, v0
	v_mov_b32_e32 v111, v0
	v_mov_b32_e32 v120, v0
	v_mov_b32_e32 v121, v0
	v_mov_b32_e32 v122, v0
	v_mov_b32_e32 v123, v0
	v_mov_b32_e32 v124, v0
	v_mov_b32_e32 v125, v0
	v_mov_b32_e32 v126, v0
	v_mov_b32_e32 v127, v0
